# v44 + nt on phase 4's read-once f32 conv-state input loads (sample items)
# speedup vs baseline: 1.0046x; 1.0046x over previous
.LBB0_1413:
	v_cmp_gt_i32_e64 s[4:5], s70, v210
	v_add_u32_e32 v2, s19, v210
	v_mov_b32_e32 v132, 0
	v_mov_b32_e32 v136, 0
	v_mov_b32_e32 v137, 0
	v_mov_b32_e32 v138, 0
	v_mov_b32_e32 v139, 0
	v_mov_b32_e32 v140, 0
	v_mov_b32_e32 v141, 0
	v_mov_b32_e32 v142, 0
	v_mov_b32_e32 v143, 0
	s_and_saveexec_b64 s[10:11], s[4:5]
	s_cbranch_execz .LBB0_1424
	v_cmp_gt_i32_e32 vcc, 3, v210
	s_and_saveexec_b64 s[12:13], vcc
	s_xor_b64 s[12:13], exec, s[12:13]
	s_cbranch_execz .LBB0_1421
	s_cmp_lt_i32 s17, 2
	s_mov_b64 s[14:15], -1
	s_cbranch_scc1 .LBB0_1419
	v_mov_b32_e32 v143, 0
	s_cmp_eq_u32 s17, 2
	v_mov_b32_e32 v142, 0
	v_mov_b32_e32 v141, 0
	v_mov_b32_e32 v140, 0
	v_mov_b32_e32 v139, 0
	v_mov_b32_e32 v138, 0
	v_mov_b32_e32 v137, 0
	v_mov_b32_e32 v136, 0
	s_cbranch_scc0 .LBB0_1418
	global_load_dwordx4 v[134:137], v[194:195], off nt
	global_load_dwordx4 v[142:145], v[194:195], off offset:16 nt
	global_load_dwordx4 v[146:149], v[194:195], off offset:32 nt
	global_load_dwordx4 v[150:153], v[194:195], off offset:48 nt
	s_waitcnt vmcnt(3)
	v_cvt_pk_bf16_f32 v140, v134, v135
	v_cvt_pk_bf16_f32 v141, v136, v137
	s_waitcnt vmcnt(2)
	v_cvt_pk_bf16_f32 v142, v142, v143
	v_cvt_pk_bf16_f32 v143, v144, v145
	s_waitcnt vmcnt(1)
	v_cvt_pk_bf16_f32 v136, v146, v147
	v_cvt_pk_bf16_f32 v137, v148, v149
	s_waitcnt vmcnt(0)
	v_cvt_pk_bf16_f32 v138, v150, v151
	v_cvt_pk_bf16_f32 v139, v152, v153

.LBB0_1424:
	s_or_b64 exec, exec, s[10:11]
	v_mov_b32_e32 v133, 0
	v_mov_b32_e32 v134, 0
	v_mov_b32_e32 v135, 0
	v_mov_b32_e32 v144, 0
	v_mov_b32_e32 v145, 0
	v_mov_b32_e32 v146, 0
	v_mov_b32_e32 v147, 0
	s_and_saveexec_b64 s[10:11], s[4:5]
	s_cbranch_execz .LBB0_1435
	v_cmp_gt_i32_e32 vcc, 2, v210
	s_and_saveexec_b64 s[12:13], vcc
	s_xor_b64 s[12:13], exec, s[12:13]
	s_cbranch_execz .LBB0_1432
	s_cmp_lt_i32 s17, 2
	s_mov_b64 s[14:15], -1
	s_cbranch_scc1 .LBB0_1430
	v_mov_b32_e32 v147, 0
	s_cmp_eq_u32 s17, 2
	v_mov_b32_e32 v146, 0
	v_mov_b32_e32 v145, 0
	v_mov_b32_e32 v144, 0
	v_mov_b32_e32 v135, 0
	v_mov_b32_e32 v134, 0
	v_mov_b32_e32 v133, 0
	v_mov_b32_e32 v132, 0
	s_cbranch_scc0 .LBB0_1429
	global_load_dwordx4 v[132:135], v[192:193], off offset:-32 nt
	global_load_dwordx4 v[146:149], v[192:193], off offset:-16 nt
	global_load_dwordx4 v[150:153], v[192:193], off nt
	global_load_dwordx4 v[154:157], v[192:193], off offset:16 nt
	s_waitcnt vmcnt(3)
	v_cvt_pk_bf16_f32 v144, v132, v133
	v_cvt_pk_bf16_f32 v145, v134, v135
	s_waitcnt vmcnt(2)
	v_cvt_pk_bf16_f32 v146, v146, v147
	v_cvt_pk_bf16_f32 v147, v148, v149
	s_waitcnt vmcnt(1)
	v_cvt_pk_bf16_f32 v132, v150, v151
	v_cvt_pk_bf16_f32 v133, v152, v153
	s_waitcnt vmcnt(0)
	v_cvt_pk_bf16_f32 v134, v154, v155
	v_cvt_pk_bf16_f32 v135, v156, v157

.LBB0_1435:
	s_or_b64 exec, exec, s[10:11]
	v_mov_b32_e32 v148, 0
	v_mov_b32_e32 v152, 0
	v_mov_b32_e32 v153, 0
	v_mov_b32_e32 v154, 0
	v_mov_b32_e32 v155, 0
	v_mov_b32_e32 v156, 0
	v_mov_b32_e32 v157, 0
	v_mov_b32_e32 v158, 0
	v_mov_b32_e32 v159, 0
	s_and_saveexec_b64 s[10:11], s[4:5]
	s_cbranch_execz .LBB0_1446
	v_cmp_gt_i32_e32 vcc, 1, v210
	s_and_saveexec_b64 s[12:13], vcc
	s_xor_b64 s[12:13], exec, s[12:13]
	s_cbranch_execz .LBB0_1443
	s_cmp_lt_i32 s17, 2
	s_mov_b64 s[14:15], -1
	s_cbranch_scc1 .LBB0_1441
	v_mov_b32_e32 v159, 0
	s_cmp_eq_u32 s17, 2
	v_mov_b32_e32 v158, 0
	v_mov_b32_e32 v157, 0
	v_mov_b32_e32 v156, 0
	v_mov_b32_e32 v155, 0
	v_mov_b32_e32 v154, 0
	v_mov_b32_e32 v153, 0
	v_mov_b32_e32 v152, 0
	s_cbranch_scc0 .LBB0_1440
	global_load_dwordx4 v[150:153], v[190:191], off offset:-32 nt
	global_load_dwordx4 v[158:161], v[190:191], off offset:-16 nt
	global_load_dwordx4 v[222:225], v[190:191], off nt
	global_load_dwordx4 v[226:229], v[190:191], off offset:16 nt
	s_waitcnt vmcnt(3)
	v_cvt_pk_bf16_f32 v156, v150, v151
	v_cvt_pk_bf16_f32 v157, v152, v153
	s_waitcnt vmcnt(2)
	v_cvt_pk_bf16_f32 v158, v158, v159
	v_cvt_pk_bf16_f32 v159, v160, v161
	s_waitcnt vmcnt(1)
	v_cvt_pk_bf16_f32 v152, v222, v223
	v_cvt_pk_bf16_f32 v153, v224, v225
	s_waitcnt vmcnt(0)
	v_cvt_pk_bf16_f32 v154, v226, v227
	v_cvt_pk_bf16_f32 v155, v228, v229

.LBB0_1446:
	s_or_b64 exec, exec, s[10:11]
	v_mov_b32_e32 v149, 0
	v_mov_b32_e32 v150, 0
	v_mov_b32_e32 v151, 0
	v_mov_b32_e32 v160, 0
	v_mov_b32_e32 v161, 0
	v_mov_b32_e32 v162, 0
	v_mov_b32_e32 v163, 0
	s_and_saveexec_b64 s[10:11], s[4:5]
	s_cbranch_execz .LBB0_1457
	v_cmp_gt_i32_e32 vcc, 0, v210
	s_and_saveexec_b64 s[12:13], vcc
	s_xor_b64 s[12:13], exec, s[12:13]
	s_cbranch_execz .LBB0_1454
	s_cmp_lt_i32 s17, 2
	s_mov_b64 s[14:15], -1
	s_cbranch_scc1 .LBB0_1452
	v_mov_b32_e32 v163, 0
	s_cmp_eq_u32 s17, 2
	v_mov_b32_e32 v162, 0
	v_mov_b32_e32 v161, 0
	v_mov_b32_e32 v160, 0
	v_mov_b32_e32 v151, 0
	v_mov_b32_e32 v150, 0
	v_mov_b32_e32 v149, 0
	v_mov_b32_e32 v148, 0
	s_cbranch_scc0 .LBB0_1451
	global_load_dwordx4 v[148:151], v[188:189], off offset:-32 nt
	global_load_dwordx4 v[222:225], v[188:189], off offset:-16 nt
	global_load_dwordx4 v[226:229], v[188:189], off nt
	global_load_dwordx4 v[230:233], v[188:189], off offset:16 nt
	s_waitcnt vmcnt(3)
	v_cvt_pk_bf16_f32 v160, v148, v149
	v_cvt_pk_bf16_f32 v161, v150, v151
	s_waitcnt vmcnt(2)
	v_cvt_pk_bf16_f32 v162, v222, v223
	v_cvt_pk_bf16_f32 v163, v224, v225
	s_waitcnt vmcnt(1)
	v_cvt_pk_bf16_f32 v148, v226, v227
	v_cvt_pk_bf16_f32 v149, v228, v229
	s_waitcnt vmcnt(0)
	v_cvt_pk_bf16_f32 v150, v230, v231
	v_cvt_pk_bf16_f32 v151, v232, v233
